# phase 0 weight conversion: next tile's loads kept in flight across the current tile's LDS transpose (vmcnt(4) after issue, vmcnt(2) before the register rotation) instead of vmcnt(0) right after the pr
# speedup vs baseline: 1.0037x; 1.0037x over previous
; DI void phase0(const Params& p, char* smem) {
;     ...
;     int item = blockIdx.x;
;     if (item < NWP) { WDECODE(item, src, N, k0, n0, Kd, up, kind, dst); WLOAD(cur, src, N, k0, n0); }
;     for (; item < NWP; item += gridDim.x) {
;       const int nitem = item + gridDim.x;
;       if (nitem < NWP) { WDECODE(nitem, nsrc, nN, nk0, nn0, nKd, nup, nkind, ndst); WLOAD(nxt, nsrc, nN, nk0, nn0); }
.LBB0_19:
	s_or_b64 exec, exec, s[6:7]
	v_lshl_add_u64 v[18:19], v[44:45], 2, v[18:19]
	v_mov_b32_e32 v51, v45
	v_or_b32_e32 v32, v68, v56
	v_lshl_add_u64 v[28:29], v[18:19], 0, v[50:51]
	v_ashrrev_i32_e32 v18, 31, v68
	v_mul_lo_u32 v20, v27, v32
	v_mul_lo_u32 v33, v26, v18
	v_mad_u64_u32 v[18:19], s[6:7], v26, v32, 0
	v_or_b32_e32 v30, 32, v32
	v_add3_u32 v19, v19, v33, v20
	v_or_b32_e32 v20, 16, v32
	v_mul_lo_u32 v51, v27, v30
	v_mad_u64_u32 v[30:31], s[6:7], v26, v30, 0
	v_or_b32_e32 v32, 48, v32
	v_mul_lo_u32 v22, v27, v20
	v_mad_u64_u32 v[20:21], s[6:7], v26, v20, 0
	v_add3_u32 v31, v31, v33, v51
	v_mul_lo_u32 v51, v27, v32
	v_mad_u64_u32 v[26:27], s[6:7], v26, v32, 0
	v_add3_u32 v21, v21, v33, v22
	v_add3_u32 v27, v27, v33, v51
	v_lshl_add_u64 v[18:19], v[18:19], 2, v[28:29]
	v_lshl_add_u64 v[22:23], v[20:21], 2, v[28:29]
	v_lshl_add_u64 v[30:31], v[30:31], 2, v[28:29]
	v_lshl_add_u64 v[32:33], v[26:27], 2, v[28:29]
	global_load_dwordx4 v[18:21], v[18:19], off
	s_nop 0
	global_load_dwordx4 v[22:25], v[22:23], off
	s_nop 0
	global_load_dwordx4 v[26:29], v[30:31], off
	s_nop 0
	global_load_dwordx4 v[30:33], v[32:33], off
	s_waitcnt vmcnt(4) lgkmcnt(0)
	s_branch .Lp0_go

; DI void phase0(const Params& p, char* smem) {
;     ...
;       for (int ps = 0; ps < 4; ++ps) {
;         int kk = (t >> 4) + 16 * ps, nn = (t & 15) * 4;
;         tile[kk * 65 + nn] = cur[ps].x; tile[kk * 65 + nn + 1] = cur[ps].y; tile[kk * 65 + nn + 2] = cur[ps].z; tile[kk * 65 + nn + 3] = cur[ps].w;
;       }
;       __syncthreads();
;       {
;         int n = t >> 2, kc = (t & 3) * 16;
;         unsigned w[8];
; #pragma unroll
;         for (int j = 0; j < 8; ++j) w[j] = pack_bf16(tile[(kc + 2 * j) * 65 + n], tile[(kc + 2 * j + 1) * 65 + n]);
;         int col = n0 + n;
;         int row = kind ? ((col >> 7) * 256 + up * 128 + (col & 127)) : col;
;         uint4* d = (uint4*)(dst + (size_t)row * Kd + k0 + kc);
;         d[0] = make_uint4(w[0], w[1], w[2], w[3]);
;         d[1] = make_uint4(w[4], w[5], w[6], w[7]);
;       }
;       __syncthreads();
; #pragma unroll
;       for (int ps = 0; ps < 4; ++ps) cur[ps] = nxt[ps];
;       src = nsrc; N = nN; k0 = nk0; n0 = nn0; Kd = nKd; up = nup; kind = nkind; dst = ndst;
.Lp0_go:
	ds_write2_b32 v61, v14, v15 offset1:1
	ds_write2_b32 v61, v16, v17 offset0:2 offset1:3
	v_add_u32_e32 v14, 0x1040, v61
	ds_write2_b32 v14, v10, v11 offset1:1
	v_add_u32_e32 v10, 0x1048, v61
	ds_write2_b32 v10, v12, v13 offset1:1
	v_add_u32_e32 v10, 0x2080, v61
	ds_write2_b32 v10, v6, v7 offset1:1
	v_add_u32_e32 v6, 0x2088, v61
	ds_write2_b32 v6, v8, v9 offset1:1
	v_add_u32_e32 v6, 0x30c0, v61
	ds_write2_b32 v6, v2, v3 offset1:1
	v_add_u32_e32 v2, 0x30c8, v61
	ds_write2_b32 v2, v4, v5 offset1:1
	s_waitcnt lgkmcnt(0)
	s_barrier
	ds_read2_b32 v[2:3], v58 offset1:130
	ds_read2_b32 v[4:5], v59 offset0:65 offset1:195
	v_add_u32_e32 v6, 0x400, v59
	v_add_u32_e32 v8, 0x800, v58
	v_add_u32_e32 v10, 0x800, v59
	ds_read2_b32 v[6:7], v6 offset0:69 offset1:199
	s_waitcnt lgkmcnt(1)
	v_cvt_pk_bf16_f32 v2, v2, v4
	v_add_u32_e32 v4, 0x400, v58
	v_cvt_pk_bf16_f32 v3, v3, v5
	ds_read2_b32 v[4:5], v4 offset0:4 offset1:134
	ds_read2_b32 v[8:9], v8 offset0:8 offset1:138
	ds_read2_b32 v[10:11], v10 offset0:73 offset1:203
	v_add_u32_e32 v12, 0xc00, v58
	v_add_u32_e32 v14, 0xc00, v59
	s_waitcnt lgkmcnt(2)
	v_cvt_pk_bf16_f32 v4, v4, v6
	v_cvt_pk_bf16_f32 v5, v5, v7
	s_waitcnt lgkmcnt(0)
	v_cvt_pk_bf16_f32 v6, v8, v10
	v_add_u32_e32 v10, v67, v57
	v_cvt_pk_bf16_f32 v7, v9, v11
	v_lshlrev_b32_e32 v11, 1, v10
	v_and_b32_e32 v11, 0x7fffff00, v11
	v_lshl_add_u32 v1, v1, 7, v11
	ds_read2_b32 v[12:13], v12 offset0:12 offset1:142
	ds_read2_b32 v[14:15], v14 offset0:77 offset1:207
	v_and_or_b32 v1, v10, s20, v1
	v_cmp_eq_u32_e32 vcc, 0, v53
	v_mov_b32_e32 v53, v45
	v_add_u32_e32 v60, s12, v60
	v_cndmask_b32_e32 v1, v1, v10, vcc
	v_mad_u64_u32 v[10:11], s[6:7], v1, v47, 0
	v_lshl_add_u64 v[10:11], v[10:11], 1, v[48:49]
	v_ashrrev_i32_e32 v47, 31, v46
	v_lshl_add_u64 v[10:11], v[46:47], 1, v[10:11]
	s_waitcnt lgkmcnt(0)
	v_cvt_pk_bf16_f32 v8, v12, v14
	v_cvt_pk_bf16_f32 v9, v13, v15
	v_lshl_add_u64 v[10:11], v[10:11], 0, v[52:53]
	global_store_dwordx4 v[10:11], v[2:5], off
	global_store_dwordx4 v[10:11], v[6:9], off offset:16
	s_andn2_b64 vcc, exec, s[4:5]
	v_mov_b32_e32 v46, v68
	v_mov_b32_e32 v67, v44
	v_mov_b32_e32 v47, v70
	v_mov_b32_e32 v1, v69
	v_mov_b32_e32 v53, v71
	v_mov_b64_e32 v[48:49], v[54:55]
	s_waitcnt vmcnt(2)
	v_mov_b64_e32 v[14:15], v[18:19]
	v_mov_b64_e32 v[16:17], v[20:21]
	v_mov_b64_e32 v[10:11], v[22:23]
	v_mov_b64_e32 v[12:13], v[24:25]
	v_mov_b64_e32 v[6:7], v[26:27]
	v_mov_b64_e32 v[8:9], v[28:29]
	v_mov_b64_e32 v[2:3], v[30:31]
	v_mov_b64_e32 v[4:5], v[32:33]
	s_barrier
	s_cbranch_vccz .LBB0_34
